# v4 + retention phase: waves 4-7 take row tiles 7..4 (thread-id xor inside the phase) so both waves of a SIMD have equal causal score work
# speedup vs baseline: 1.0470x; 1.0030x over previous
; #define LAS __attribute__((address_space(3)))
; __device__ __forceinline__ void retention_fused(const Params& p, LAS unsigned char* lds, int unit) {
;     const int tid = threadIdx.x, lane = tid & 63, wid = __builtin_amdgcn_readfirstlane(tid >> 6), fr = lane & 15, fq = lane >> 4;
;     const int b = unit >> 5, h = (unit >> 3) & 3, vb = unit & 7;
;     unsigned char* ws = p.ws;
;     const bf16_t* Qg = (const bf16_t*)(ws + WS_Q) + (size_t)b * SEQ * D + h * 256;
;     const bf16_t* Kg = (const bf16_t*)(ws + WS_K) + (size_t)b * SEQ * D + h * 256;
;     const bf16_t* Vg = (const bf16_t*)(ws + WS_V) + (size_t)b * SEQ * VD + h * 512 + vb * 64;
;     bf16_t* Og = (bf16_t*)(ws + WS_O) + (size_t)b * SEQ * VD + h * 512 + vb * 64;
;     const float log2g = __log2f(1.0f - exp2f(-5.0f - (float)h));
;     const float gC = exp2f(128.0f * log2g);
;     f32x4 S[2][4];
; #pragma unroll
;     for (int mt = 0; mt < 2; ++mt)
; #pragma unroll
;         for (int nt = 0; nt < 4; ++nt) S[mt][nt] = (f32x4){0.f, 0.f, 0.f, 0.f};
;     LAS unsigned char* Ks = lds + LDS_KS; LAS unsigned char* Vs = lds + LDS_VS; LAS unsigned char* Vw = lds + LDS_VW; LAS unsigned char* St = lds + LDS_ST;
;     LAS f32x4* qs = (LAS f32x4*)(lds + LDS_FQ); LAS f32x4* kws = (LAS f32x4*)(lds + LDS_FK); LAS float* asc = (LAS float*)(lds + LDS_FA); LAS float* red = (LAS float*)(lds + 0);
;     const int v4 = tid & 127, rg = tid >> 7;
;     u32x2 vjp[4]; f32x4 oa[4];
;     const float* S0 = nullptr; float* S1 = nullptr; bf16_t* Ogs = nullptr;
;     float sg = 0.f, sg2 = 0.f, sg3 = 0.f, sg4 = 0.f;
; #pragma unroll
;     for (int i = 0; i < 4; ++i) { vjp[i] = (u32x2){0u, 0u}; oa[i] = (f32x4){0.f, 0.f, 0.f, 0.f}; }
.LBB0_1034:
	s_and_b64 vcc, exec, s[0:1]
	s_cbranch_vccz .LBB0_1059
	v_and_b32_e32 v248, 0x100, v146
	v_lshrrev_b32_e32 v249, 1, v248
	v_lshrrev_b32_e32 v248, 2, v248
	v_or_b32_e32 v248, v248, v249
	v_xor_b32_e32 v146, v146, v248
	s_ashr_i32 s16, s78, 5
	s_bfe_u32 s33, s78, 0x20003
	s_ashr_i32 s17, s16, 31
	s_add_u32 s10, s74, 0xc009000
	s_addc_u32 s11, s75, 0
	s_lshl_b64 s[0:1], s[16:17], 22
	s_add_u32 s2, s10, s0
	s_addc_u32 s3, s11, s1
	s_lshl_b32 s8, s33, 9
	s_add_u32 s2, s2, s8
	s_addc_u32 s3, s3, 0
	s_lshl_b32 s4, s78, 6
	s_and_b32 s36, s4, 0x1c0
	s_add_u32 s12, s74, 0x16509000
	s_addc_u32 s13, s75, 0
	s_lshl_b64 s[4:5], s[16:17], 23
	v_cvt_f32_ubyte0_e32 v1, s33
	s_add_u32 s6, s12, s4
	v_sub_f32_e32 v1, 0xc0a00000, v1
	s_mov_b32 s15, 0xc2fc0000
	s_addc_u32 s7, s13, s5
	s_lshl_b32 s9, s33, 10
	v_mov_b32_e32 v4, 0x42800000
	v_cmp_gt_f32_e32 vcc, s15, v1
	s_add_u32 s14, s6, s9
	s_addc_u32 s18, s7, 0
	v_cndmask_b32_e32 v2, 0, v4, vcc
	v_add_f32_e32 v1, v1, v2
	v_exp_f32_e32 v1, v1
	s_and_b64 s[6:7], vcc, exec
	v_readfirstlane_b32 s22, v146
	s_cselect_b32 s6, 0xffffffc0, 0
	s_lshr_b32 s17, s22, 6
	s_add_u32 s20, s74, 0x9f09000
	s_addc_u32 s21, s75, 0
	v_ldexp_f32 v1, v1, s6
	s_add_u32 s6, s20, s0
	s_addc_u32 s7, s21, s1
	s_add_u32 s23, s74, 0xe109000
	v_sub_f32_e32 v1, 1.0, v1
	s_addc_u32 s24, s75, 0
	v_log_f32_e32 v153, v1
	s_add_u32 s0, s23, s4
	s_addc_u32 s1, s24, s5
	s_add_u32 s9, s0, s9
	s_addc_u32 s25, s1, 0
	s_lshl_b32 s26, s36, 1
	v_mul_f32_e32 v1, 0x43000000, v153
	s_add_u32 s0, s14, s26
	s_addc_u32 s1, s18, 0
	v_cmp_gt_f32_e32 vcc, s15, v1
	s_add_u32 s4, s6, s8
	s_addc_u32 s5, s7, 0
	v_cndmask_b32_e32 v1, 0, v4, vcc
	v_fmac_f32_e32 v1, 0x43000000, v153
	s_add_u32 s6, s9, s26
	v_exp_f32_e32 v1, v1
	s_addc_u32 s7, s25, 0
	v_and_b32_e32 v2, 31, v146
	s_and_b64 s[8:9], vcc, exec
	v_lshlrev_b32_e32 v118, 4, v2
	v_mov_b32_e32 v119, 0
	v_and_b32_e32 v2, 7, v146
	v_and_b32_e32 v114, 15, v146
	s_cselect_b32 s8, 0xffffffc0, 0
	v_lshl_add_u64 v[120:121], s[2:3], 0, v[118:119]
	v_add_u32_e32 v15, 0, v118
	v_lshlrev_b32_e32 v118, 4, v2
	v_lshlrev_b32_e32 v2, 3, v146
	v_ldexp_f32 v116, v1, s8
	s_and_b32 s8, s22, 0xffffffc0
	v_and_b32_e32 v18, 24, v2
	v_lshlrev_b32_e32 v2, 1, v114
	v_mov_b32_e32 v3, v119
	v_lshl_add_u64 v[126:127], s[0:1], 0, v[2:3]
	s_add_i32 s0, s8, 0
	s_add_i32 s9, 0, 0x19000
	s_add_i32 s2, 0, 0x10800
	v_add_u32_e32 v19, s0, v18
	s_and_b32 s0, s78, 3
	v_bfe_u32 v9, v146, 4, 2
	s_add_i32 s18, s9, s8
	v_add_u32_e32 v184, s2, v118
	s_add_i32 s2, 0, 0x14c00
	s_lshl_b32 s37, s17, 4
	s_lshl_b32 s1, s0, 9
	v_lshlrev_b32_e32 v1, 3, v9
	v_bfe_u32 v17, v146, 2, 2
	s_add_u32 s38, s20, s1
	v_add_u32_e32 v14, s18, v1
	v_or_b32_e32 v3, v1, v17
	s_addc_u32 s39, s21, 0
	v_cvt_f32_ubyte0_e32 v1, s0
	s_add_u32 s40, s10, s1
	v_sub_f32_e32 v1, 0xc0a00000, v1
	v_lshl_add_u64 v[122:123], s[6:7], 0, v[118:119]
	v_add_u32_e32 v185, s2, v118
	v_and_b32_e32 v118, 48, v146
	s_addc_u32 s41, s11, 0
	s_lshl_b32 s1, s0, 10
	v_cmp_gt_f32_e32 vcc, s15, v1
	v_lshl_add_u64 v[124:125], s[4:5], 0, v[118:119]
	s_add_u32 s4, s23, s1
	v_cndmask_b32_e32 v2, 0, v4, vcc
	s_addc_u32 s5, s24, 0
	v_add_f32_e32 v1, v1, v2
	s_add_u32 s42, s12, s1
	v_exp_f32_e32 v1, v1
	s_addc_u32 s43, s13, 0
	s_and_b64 s[0:1], vcc, exec
	s_cselect_b32 s0, 0xffffffc0, 0
	v_ldexp_f32 v1, v1, s0
	v_and_b32_e32 v5, 0x7f, v146
	v_sub_f32_e32 v131, 1.0, v1
	v_lshlrev_b32_e32 v1, 4, v146
	s_add_i32 s44, 0, 0x21400
	s_add_i32 s45, 0, 0x22400
	v_add_u32_e32 v187, s44, v1
	v_add_u32_e32 v188, s45, v1
	v_lshlrev_b32_e32 v10, 3, v5
	v_mov_b32_e32 v11, v119
	v_lshrrev_b32_e32 v1, 5, v146
	v_lshl_add_u64 v[136:137], s[4:5], 0, v[10:11]
	v_lshlrev_b32_e32 v191, 10, v1
	v_mul_u32_u24_e32 v11, 0x210, v1
	v_add_u32_e32 v1, 0x200, v146
	v_lshrrev_b32_e32 v12, 5, v1
	v_lshlrev_b32_e32 v192, 10, v12
	v_mul_u32_u24_e32 v21, 0x210, v12
	v_add_u32_e32 v12, 0x600, v146
	v_lshrrev_b32_e32 v12, 5, v12
	v_lshlrev_b32_e32 v194, 10, v12
	v_mul_u32_u24_e32 v22, 0x210, v12
	v_add_u32_e32 v12, 0xa00, v146
	v_lshrrev_b32_e32 v12, 5, v12
	v_lshlrev_b32_e32 v196, 10, v12
	v_mul_u32_u24_e32 v23, 0x210, v12
	v_add_u32_e32 v12, 0xe00, v146
	v_lshrrev_b32_e32 v12, 5, v12
	v_mul_f32_e32 v133, v131, v131
	v_lshlrev_b32_e32 v198, 10, v12
	v_mul_u32_u24_e32 v24, 0x210, v12
	v_lshrrev_b32_e32 v12, 3, v146
	v_lshrrev_b32_e32 v1, 3, v1
	v_mov_b32_e32 v2, v133
	v_mov_b32_e32 v130, v133
	v_lshlrev_b32_e32 v199, 11, v12
	v_mul_u32_u24_e32 v200, 0x88, v12
	v_xor_b32_e32 v12, 0x7f, v12
	v_sub_u32_e32 v13, 0x7f, v1
	v_pk_mul_f32 v[134:135], v[2:3], v[130:131] op_sel_hi:[0,1]
	v_cvt_f32_ubyte0_e32 v12, v12
	v_cvt_f32_i32_e32 v13, v13
	v_lshlrev_b32_e32 v130, 2, v9
	v_mul_f32_e32 v12, v153, v12
	v_or_b32_e32 v203, s37, v130
	v_exp_f32_e32 v140, v12
	v_or_b32_e32 v12, 1, v203
	v_cvt_f32_u32_e32 v12, v12
	v_lshlrev_b32_e32 v201, 11, v1
	v_mul_u32_u24_e32 v202, 0x88, v1
	v_mul_f32_e32 v1, v153, v13
	v_or_b32_e32 v13, 2, v203
	v_cvt_f32_u32_e32 v13, v13
	v_exp_f32_e32 v142, v1
	v_mul_f32_e32 v1, v153, v12
	v_or_b32_e32 v12, 3, v203
	v_cvt_f32_u32_e32 v12, v12
	v_exp_f32_e32 v144, v1
	v_mul_f32_e32 v1, v153, v13
	v_add_u32_e32 v13, 4, v203
	v_cvt_f32_u32_e32 v13, v13
	v_exp_f32_e32 v145, v1
	v_mul_f32_e32 v1, v153, v12
	v_exp_f32_e32 v148, v1
	v_sub_u32_e32 v1, v114, v130
	v_mul_f32_e32 v12, v153, v13
	v_cvt_f32_i32_e32 v13, v1
	v_or_b32_e32 v1, 1, v130
	v_sub_u32_e32 v25, v114, v1
	v_cvt_f32_i32_e32 v25, v25
	v_or_b32_e32 v152, 2, v130
	s_waitcnt lgkmcnt(0)
; #define LAS __attribute__((address_space(3)))
; __device__ __forceinline__ void retention_fused(const Params& p, LAS unsigned char* lds, int unit) {
;     ...
;     const float log2g = __log2f(1.0f - exp2f(-5.0f - (float)h));
;     const float gC = exp2f(128.0f * log2g);
;     f32x4 S[2][4];
; #pragma unroll
;     for (int mt = 0; mt < 2; ++mt)
; #pragma unroll
;         for (int nt = 0; nt < 4; ++nt) S[mt][nt] = (f32x4){0.f, 0.f, 0.f, 0.f};
;     LAS unsigned char* Ks = lds + LDS_KS; LAS unsigned char* Vs = lds + LDS_VS; LAS unsigned char* Vw = lds + LDS_VW; LAS unsigned char* St = lds + LDS_ST;
;     LAS f32x4* qs = (LAS f32x4*)(lds + LDS_FQ); LAS f32x4* kws = (LAS f32x4*)(lds + LDS_FK); LAS float* asc = (LAS float*)(lds + LDS_FA); LAS float* red = (LAS float*)(lds + 0);
;     const int v4 = tid & 127, rg = tid >> 7;
;     u32x2 vjp[4]; f32x4 oa[4];
;     const float* S0 = nullptr; float* S1 = nullptr; bf16_t* Ogs = nullptr;
;     float sg = 0.f, sg2 = 0.f, sg3 = 0.f, sg4 = 0.f;
; #pragma unroll
;     for (int i = 0; i < 4; ++i) { vjp[i] = (u32x2){0u, 0u}; oa[i] = (f32x4){0.f, 0.f, 0.f, 0.f}; }
	v_exp_f32_e32 v149, v12
	v_mul_f32_e32 v12, v153, v13
	v_or_b32_e32 v115, 3, v130
	v_sub_u32_e32 v13, v114, v152
	v_exp_f32_e32 v150, v12
	v_mul_f32_e32 v12, v153, v25
	v_cvt_f32_i32_e32 v13, v13
	v_sub_u32_e32 v25, v114, v115
	v_cvt_f32_i32_e32 v25, v25
	s_lshr_b32 s23, s22, 5
	s_lshr_b32 s18, s22, 7
	s_lshl_b32 s22, s22, 5
	s_and_b32 s26, s22, 0x800
	s_add_i32 s46, 0, 0x23400
	s_lshl_b32 s22, s17, 3
	v_exp_f32_e32 v151, v12
	v_mul_f32_e32 v12, v153, v13
	s_add_i32 s47, s46, s22
	s_or_b32 s22, s23, 1
	v_exp_f32_e32 v154, v12
	v_mul_f32_e32 v12, v153, v25
	v_lshrrev_b32_e32 v183, 7, v146
	v_lshlrev_b32_e32 v138, 4, v5
	s_lshl_b32 s23, s22, 10
	s_lshl_b32 s22, s22, 2
	v_exp_f32_e32 v155, v12
	v_mov_b32_e32 v139, v119
	s_mov_b32 s19, 0
	s_movk_i32 s14, 0x7f
	v_and_b32_e32 v7, 63, v146
	v_or_b32_e32 v2, 0x800, v146
	v_lshl_add_u32 v189, v183, 13, 0
	s_movk_i32 s4, 0xe800
	s_and_b32 s27, s23, 0xc00
	s_add_i32 s48, s46, s22
	v_readlane_b32 s52, v247, 0
	v_lshl_add_u64 v[12:13], s[72:73], 0, v[138:139]
	s_mov_b64 s[22:23], 0x5310000
	v_add_u32_e32 v16, s9, v118
	v_add_u32_e32 v20, s2, v18
	s_movk_i32 s0, 0x100
	v_or_b32_e32 v4, 0xc00, v146
	s_lshl_b64 s[20:21], s[18:19], 11
	v_lshlrev_b32_e32 v6, 2, v7
	v_cmp_eq_u32_e64 s[2:3], 0, v7
	v_lshlrev_b32_e32 v8, 2, v5
	v_lshlrev_b32_e32 v10, 11, v183
	v_mad_i32_i24 v5, v183, s4, v189
	s_movk_i32 s4, 0x80
	v_cmp_lt_u32_e64 s[6:7], s14, v146
	s_movk_i32 s12, 0xff
	s_movk_i32 s14, 0x17f
	s_movk_i32 s24, 0x210
	v_mul_u32_u24_e32 v7, 0x210, v114
	v_mul_u32_u24_e32 v25, 0x210, v3
	v_mul_u32_u24_e32 v3, 0x88, v3
	v_readlane_b32 s53, v247, 1
	v_readlane_b32 s54, v247, 2
	v_readlane_b32 s55, v247, 3
	v_readlane_b32 s56, v247, 4
	v_readlane_b32 s57, v247, 5
	v_readlane_b32 s58, v247, 6
	v_readlane_b32 s59, v247, 7
	v_lshl_add_u64 v[158:159], v[12:13], 0, s[22:23]
	s_lshl_b32 s50, s18, 1
	v_mul_u32_u24_e32 v9, 0x220, v9
	v_mul_u32_u24_e32 v12, 0x88, v17
	s_mov_b32 s18, s19
	v_lshlrev_b32_e32 v206, 1, v2
	v_mbcnt_lo_u32_b32 v2, -1, 0
	v_or_b32_e32 v186, s37, v114
	v_mov_b32_e32 v128, v116
	v_mov_b32_e32 v129, v116
	v_cmp_gt_u32_e64 s[0:1], s0, v146
	v_cmp_gt_u32_e64 s[4:5], s4, v146
	v_cmp_eq_u32_e64 s[8:9], 1, v183
	v_cmp_eq_u32_e64 s[10:11], 2, v183
	v_lshlrev_b32_e32 v190, 4, v183
	v_cmp_lt_u32_e64 s[12:13], s12, v146
	v_cmp_lt_u32_e64 s[14:15], s14, v146
	s_mov_b32 s49, 0x8000
	v_or_b32_e32 v193, 0x8000, v191
	v_or_b32_e32 v195, 0x10000, v191
	v_or_b32_e32 v197, 0x18000, v191
	v_lshl_add_u64 v[156:157], s[58:59], 0, v[138:139]
	v_mov_b32_e32 v141, v140
	v_mov_b32_e32 v143, v142
	v_mov_b32_e32 v132, v135
	v_mad_u32_u24 v139, v114, s24, v118
	s_add_i32 s50, s50, 2
	v_add3_u32 v204, v9, v12, v18
	v_mov_b64_e32 v[164:165], 0
	s_mov_b64 s[24:25], 0
	v_mov_b64_e32 v[168:169], s[18:19]
	s_movk_i32 s51, 0x4000
	v_lshlrev_b32_e32 v205, 1, v146
	v_lshlrev_b32_e32 v207, 1, v4
	v_lshlrev_b32_e32 v118, 1, v6
	s_lshl_b32 s18, s26, 1
	s_lshl_b32 s22, s27, 1
	s_movk_i32 s52, 0x2000
	v_add_u32_e32 v208, v14, v7
	v_add_u32_e32 v209, v15, v11
	v_add_u32_e32 v210, v15, v21
	v_add_u32_e32 v211, v15, v22
	v_add_u32_e32 v212, v15, v23
	v_add_u32_e32 v213, v15, v24
	s_movk_i32 s53, 0x6000
	v_add_u32_e32 v214, v16, v7
	s_mov_b32 s54, 0xa000
	s_mov_b32 s55, 0xc000
	s_mov_b32 s56, 0xe000
	v_add_u32_e32 v215, v19, v25
	v_add_u32_e32 v216, v20, v3
	v_add_u32_e32 v217, v5, v138
	v_lshlrev_b32_e32 v160, 1, v10
	v_lshlrev_b32_e32 v162, 1, v8
	v_mbcnt_hi_u32_b32 v218, -1, v2
	v_mov_b64_e32 v[166:167], 0
	v_mov_b32_e32 v219, v119
	v_mov_b32_e32 v220, v119
	s_mov_b32 s57, s19
	v_mov_b32_e32 v30, v119
	v_mov_b32_e32 v31, v119
	v_mov_b32_e32 v32, v119
	v_mov_b32_e32 v33, v119
	v_mov_b32_e32 v18, v119
	v_mov_b32_e32 v19, v119
	v_mov_b32_e32 v20, v119
	v_mov_b32_e32 v21, v119
	v_mov_b32_e32 v22, v119
	v_mov_b32_e32 v23, v119
	v_mov_b32_e32 v24, v119
	v_mov_b32_e32 v25, v119
	v_mov_b32_e32 v26, v119
	v_mov_b32_e32 v27, v119
	v_mov_b32_e32 v28, v119
	v_mov_b32_e32 v29, v119
	v_mov_b32_e32 v2, v119
	v_mov_b32_e32 v3, v119
	v_mov_b32_e32 v4, v119
	v_mov_b32_e32 v5, v119
	v_mov_b32_e32 v6, v119
	v_mov_b32_e32 v7, v119
	v_mov_b32_e32 v8, v119
	v_mov_b32_e32 v9, v119
	v_mov_b32_e32 v10, v119
	v_mov_b32_e32 v11, v119
	v_mov_b32_e32 v12, v119
	v_mov_b32_e32 v13, v119
	v_mov_b32_e32 v14, v119
	v_mov_b32_e32 v15, v119
	v_mov_b32_e32 v16, v119
	v_mov_b32_e32 v17, v119
	v_mov_b32_e32 v34, v119
	v_mov_b32_e32 v35, v119
	v_mov_b32_e32 v36, v119
	v_mov_b32_e32 v37, v119
	v_mov_b32_e32 v38, v119
	v_mov_b32_e32 v39, v119
	v_mov_b32_e32 v40, v119
	v_mov_b32_e32 v41, v119
	v_mov_b32_e32 v42, v119
	v_mov_b32_e32 v43, v119
	v_mov_b32_e32 v44, v119
	v_mov_b32_e32 v45, v119
	v_mov_b32_e32 v46, v119
	v_mov_b32_e32 v47, v119
	v_mov_b32_e32 v48, v119
	v_mov_b32_e32 v49, v119
	v_mov_b32_e32 v170, v119
	v_mov_b32_e32 v171, v119
	v_mov_b32_e32 v172, v119
	v_mov_b32_e32 v173, v119
	v_mov_b32_e32 v174, v119
	v_mov_b32_e32 v175, v119
	v_mov_b32_e32 v176, v119
	v_mov_b32_e32 v177, v119
	v_readlane_b32 s60, v247, 8
	v_readlane_b32 s61, v247, 9
	v_readlane_b32 s62, v247, 10
	v_readlane_b32 s63, v247, 11
	v_readlane_b32 s64, v247, 12
	v_readlane_b32 s65, v247, 13
	v_readlane_b32 s66, v247, 14
	v_readlane_b32 s67, v247, 15
	s_branch .LBB0_1038

; #define LAS __attribute__((address_space(3)))
; __device__ __forceinline__ void retention_fused(const Params& p, LAS unsigned char* lds, int unit) {
;     ...
;     float* So = p.out + OUT_RETP + ((size_t)(b * 4 + h) * 256) * 512 + vb * 64;
; #pragma unroll
;     for (int mt = 0; mt < 2; ++mt)
; #pragma unroll
;         for (int nt = 0; nt < 4; ++nt)
; #pragma unroll
;             for (int r = 0; r < 4; ++r) So[(size_t)(32 * wid + 16 * mt + fq * 4 + r) * 512 + nt * 16 + fr] = S[mt][nt][r];
; }
; __device__ __forceinline__ void phase_retention(const Params& p, LAS unsigned char* lds, int vcu, int G) {
;     if (G == 256) { retention_fused(p, lds, vcu); __syncthreads(); return; }
.LBB0_1058:
	s_lshl_b32 s0, s16, 2
	s_or_b32 s0, s0, s33
	s_ashr_i32 s1, s0, 31
	s_lshl_b64 s[0:1], s[0:1], 19
	s_add_u32 s0, s72, s0
	s_addc_u32 s1, s73, s1
	s_lshl_b32 s2, s36, 2
	s_add_u32 s0, s0, s2
	s_addc_u32 s1, s1, 0
	v_lshl_or_b32 v34, s17, 5, v130
	v_lshlrev_b32_e32 v36, 2, v114
	v_mov_b32_e32 v37, 0
	v_lshl_add_u64 v[38:39], s[0:1], 0, v[36:37]
	s_mov_b64 s[0:1], 0x4310000
	v_mov_b32_e32 v35, v37
	v_or_b32_e32 v36, 1, v34
	v_lshl_add_u64 v[38:39], v[38:39], 0, s[0:1]
	v_lshlrev_b64 v[40:41], 11, v[34:35]
	v_lshlrev_b64 v[42:43], 11, v[36:37]
	v_lshl_add_u64 v[40:41], v[38:39], 0, v[40:41]
	v_lshl_add_u64 v[42:43], v[38:39], 0, v[42:43]
	v_or_b32_e32 v36, 2, v34
	global_store_dword v[40:41], v30, off
	global_store_dword v[42:43], v31, off
	v_lshlrev_b64 v[30:31], 11, v[36:37]
	v_or_b32_e32 v36, 3, v34
	v_lshlrev_b64 v[44:45], 11, v[36:37]
	v_lshl_add_u64 v[30:31], v[38:39], 0, v[30:31]
	v_lshl_add_u64 v[44:45], v[38:39], 0, v[44:45]
	v_or_b32_e32 v36, 16, v34
	global_store_dword v[30:31], v32, off
	global_store_dword v[44:45], v33, off
	global_store_dword v[40:41], v18, off offset:64
	global_store_dword v[42:43], v19, off offset:64
	global_store_dword v[30:31], v20, off offset:64
	global_store_dword v[44:45], v21, off offset:64
	global_store_dword v[40:41], v22, off offset:128
	global_store_dword v[42:43], v23, off offset:128
	global_store_dword v[30:31], v24, off offset:128
	global_store_dword v[44:45], v25, off offset:128
	global_store_dword v[40:41], v26, off offset:192
	global_store_dword v[42:43], v27, off offset:192
	global_store_dword v[30:31], v28, off offset:192
	global_store_dword v[44:45], v29, off offset:192
	v_lshlrev_b64 v[18:19], 11, v[36:37]
	v_or_b32_e32 v36, 17, v34
	v_lshlrev_b64 v[20:21], 11, v[36:37]
	v_lshl_add_u64 v[18:19], v[38:39], 0, v[18:19]
	v_lshl_add_u64 v[20:21], v[38:39], 0, v[20:21]
	v_or_b32_e32 v36, 18, v34
	global_store_dword v[18:19], v2, off
	global_store_dword v[20:21], v3, off
	v_lshlrev_b64 v[2:3], 11, v[36:37]
	v_or_b32_e32 v36, 19, v34
	v_lshlrev_b64 v[22:23], 11, v[36:37]
	v_lshl_add_u64 v[2:3], v[38:39], 0, v[2:3]
	v_lshl_add_u64 v[22:23], v[38:39], 0, v[22:23]
	global_store_dword v[2:3], v4, off
	global_store_dword v[22:23], v5, off
	global_store_dword v[18:19], v6, off offset:64
	global_store_dword v[20:21], v7, off offset:64
	global_store_dword v[2:3], v8, off offset:64
	global_store_dword v[22:23], v9, off offset:64
	global_store_dword v[18:19], v10, off offset:128
	global_store_dword v[20:21], v11, off offset:128
	global_store_dword v[2:3], v12, off offset:128
	global_store_dword v[22:23], v13, off offset:128
	global_store_dword v[18:19], v14, off offset:192
	global_store_dword v[20:21], v15, off offset:192
	global_store_dword v[2:3], v16, off offset:192
	global_store_dword v[22:23], v17, off offset:192
	s_barrier
	v_and_b32_e32 v248, 0x100, v146
	v_lshrrev_b32_e32 v249, 1, v248
	v_lshrrev_b32_e32 v248, 2, v248
	v_or_b32_e32 v248, v248, v249
	v_xor_b32_e32 v146, v146, v248
